# hand-written final rmsnorm row kernels (P2 tail filler for group 0 and the last phase for group 1)
# speedup vs baseline: 1.0114x; 1.0079x over previous
; DEV int tidx() { return tidx_full() & 255; }
; DEV void final_norm_rows(float* __restrict__ X, const float* __restrict__ gvec, int rbeg) {
;   const int tid = tidx();
;   const int wave = tid >> 6, lane = tid & 63;
;   for (int jb = 0; jb < 16; jb += 4) {
;     float4 v[4][4];
;     float ss[4];
; #pragma unroll
;     for (int j = 0; j < 4; ++j) {
;       const float* x = X + (long)(rbeg + wave + 4 * (jb + j)) * D;
; #pragma unroll
;       for (int i = 0; i < 4; ++i) v[j][i] = *(const float4*)(x + lane * 4 + 256 * i);
;     }
; #pragma unroll
;     for (int j = 0; j < 4; ++j) {
;       float t = 0.f;
; #pragma unroll
;       for (int i = 0; i < 4; ++i) t += v[j][i].x * v[j][i].x + v[j][i].y * v[j][i].y + v[j][i].z * v[j][i].z + v[j][i].w * v[j][i].w;
;       ss[j] = wave_sum(t);
;     }
; #pragma unroll
;     for (int j = 0; j < 4; ++j) {
;       float* x = X + (long)(rbeg + wave + 4 * (jb + j)) * D;
;       const float rstd = rsqrtf(ss[j] * (1.f / 1024.f) + EPSF);
; #pragma unroll
;       for (int i = 0; i < 4; ++i) {
;         const int k = lane * 4 + 256 * i;
;         const float4 g = *(const float4*)(gvec + k);
;         *(float4*)(x + k) = make_float4(v[j][i].x * rstd * g.x, v[j][i].y * rstd * g.y, v[j][i].z * rstd * g.z, v[j][i].w * rstd * g.w);
;       }
;     }
;   }
; }
; DEV void phase_p2_naive(const Params& p, int g, char* hsm) {
;     ...
;   for (;;) {
;     __syncthreads();
;     if (threadIdx.x == 0) s_item = (int)atomicAdd(cnt2, 2u);
;     __syncthreads();
;     const int it = s_item + half;
;     if (it >= 512) break;
;     if (g == 0) norm_adaln_rows(p.in[I_XS], p.in[I_N1G], mod, 8, 8192, 0, 1024, (u16*)(p.out + (size_t)NTOK * D), it * 64);
;     else final_norm_rows(p.out, p.in[I_FING], it * 64);
.LBB0_813:
	s_or_b64 exec, exec, s[0:1]
	s_waitcnt lgkmcnt(0)
	s_barrier
	ds_read_b32 v0, v207
	s_mov_b64 s[0:1], -1
	s_waitcnt lgkmcnt(0)
	v_readfirstlane_b32 s4, v0
	s_add_i32 s4, s4, s26
	s_cmpk_gt_i32 s4, 0x1ff
	s_cbranch_scc1 .LBB0_808
	v_readlane_b32 s6, v252, 12
	v_readlane_b32 s7, v252, 13
	s_lshl_b32 s4, s4, 6
	s_and_b64 vcc, exec, s[6:7]
	s_cbranch_vccz .LBB0_818
	v_readfirstlane_b32 s5, v202
	s_bfe_u32 s5, s5, 0x20006
	s_add_u32 s4, s4, s5
	v_mov_b32_e32 v53, 0x358637bd
	v_and_b32_e32 v51, 63, v202
	v_lshlrev_b32_e32 v51, 4, v51
	global_load_dwordx4 v[32:35], v51, s[76:77]
	global_load_dwordx4 v[36:39], v51, s[76:77] offset:1024
	global_load_dwordx4 v[40:43], v51, s[76:77] offset:2048
	global_load_dwordx4 v[44:47], v51, s[76:77] offset:3072
	s_lshl_b32 s5, s4, 12
	s_add_u32 s6, s78, s5
	s_addc_u32 s7, s79, 0
	s_lshl_b32 s5, s4, 12
	s_add_u32 s0, s78, s5
	s_addc_u32 s1, s79, 0
	global_load_dwordx4 v[0:3], v51, s[0:1]
	global_load_dwordx4 v[4:7], v51, s[0:1] offset:1024
	global_load_dwordx4 v[8:11], v51, s[0:1] offset:2048
	global_load_dwordx4 v[12:15], v51, s[0:1] offset:3072
	s_add_u32 s4, s4, 0x4
	s_lshl_b32 s5, s4, 12
	s_add_u32 s0, s78, s5
	s_addc_u32 s1, s79, 0
	global_load_dwordx4 v[16:19], v51, s[0:1]
	global_load_dwordx4 v[20:23], v51, s[0:1] offset:1024
	global_load_dwordx4 v[24:27], v51, s[0:1] offset:2048
	global_load_dwordx4 v[28:31], v51, s[0:1] offset:3072
	s_add_u32 s4, s4, 0x4
	s_mov_b32 s8, 0
.Lffill_loop:
	s_waitcnt vmcnt(4)
	v_mul_f32_e32 v48, v0, v0
	v_fmac_f32_e32 v48, v1, v1
	v_fmac_f32_e32 v48, v2, v2
	v_fmac_f32_e32 v48, v3, v3
	v_fmac_f32_e32 v48, v4, v4
	v_fmac_f32_e32 v48, v5, v5
	v_fmac_f32_e32 v48, v6, v6
	v_fmac_f32_e32 v48, v7, v7
	v_fmac_f32_e32 v48, v8, v8
	v_fmac_f32_e32 v48, v9, v9
	v_fmac_f32_e32 v48, v10, v10
	v_fmac_f32_e32 v48, v11, v11
	v_fmac_f32_e32 v48, v12, v12
	v_fmac_f32_e32 v48, v13, v13
	v_fmac_f32_e32 v48, v14, v14
	v_fmac_f32_e32 v48, v15, v15
	s_nop 1
	v_add_f32_dpp v48, v48, v48 quad_perm:[1,0,3,2] row_mask:0xf bank_mask:0xf
	s_nop 1
	v_add_f32_dpp v48, v48, v48 quad_perm:[2,3,0,1] row_mask:0xf bank_mask:0xf
	s_nop 1
	v_add_f32_dpp v48, v48, v48 row_half_mirror row_mask:0xf bank_mask:0xf
	s_nop 1
	v_add_f32_dpp v48, v48, v48 row_mirror row_mask:0xf bank_mask:0xf
	s_nop 1
	v_add_f32_dpp v48, v48, v48 row_bcast:15 row_mask:0xa bank_mask:0xf
	s_nop 1
	v_add_f32_dpp v48, v48, v48 row_bcast:31 row_mask:0xc bank_mask:0xf
	s_nop 1
	v_readlane_b32 s5, v48, 63
	v_mov_b32_e32 v49, 0x3a800000
	s_nop 1
	v_fma_f32 v52, s5, v49, v53
	v_cmp_gt_f32_e32 vcc, 0x800000, v52
	v_mul_f32_e32 v50, 0x4b800000, v52
	v_cndmask_b32_e32 v52, v52, v50, vcc
	v_rsq_f32_e32 v52, v52
	s_nop 0
	v_mul_f32_e32 v50, 0x45800000, v52
	v_cndmask_b32_e32 v52, v52, v50, vcc
	v_mul_f32_e32 v0, v0, v52
	v_mul_f32_e32 v0, v0, v32
	v_mul_f32_e32 v1, v1, v52
	v_mul_f32_e32 v1, v1, v33
	v_mul_f32_e32 v2, v2, v52
	v_mul_f32_e32 v2, v2, v34
	v_mul_f32_e32 v3, v3, v52
	v_mul_f32_e32 v3, v3, v35
	v_mul_f32_e32 v4, v4, v52
	v_mul_f32_e32 v4, v4, v36
	v_mul_f32_e32 v5, v5, v52
	v_mul_f32_e32 v5, v5, v37
	v_mul_f32_e32 v6, v6, v52
	v_mul_f32_e32 v6, v6, v38
	v_mul_f32_e32 v7, v7, v52
	v_mul_f32_e32 v7, v7, v39
	v_mul_f32_e32 v8, v8, v52
	v_mul_f32_e32 v8, v8, v40
	v_mul_f32_e32 v9, v9, v52
	v_mul_f32_e32 v9, v9, v41
	v_mul_f32_e32 v10, v10, v52
	v_mul_f32_e32 v10, v10, v42
	v_mul_f32_e32 v11, v11, v52
	v_mul_f32_e32 v11, v11, v43
	v_mul_f32_e32 v12, v12, v52
	v_mul_f32_e32 v12, v12, v44
	v_mul_f32_e32 v13, v13, v52
	v_mul_f32_e32 v13, v13, v45
	v_mul_f32_e32 v14, v14, v52
	v_mul_f32_e32 v14, v14, v46
	v_mul_f32_e32 v15, v15, v52
	v_mul_f32_e32 v15, v15, v47
	global_store_dwordx4 v51, v[0:3], s[6:7]
	global_store_dwordx4 v51, v[4:7], s[6:7] offset:1024
	global_store_dwordx4 v51, v[8:11], s[6:7] offset:2048
	global_store_dwordx4 v51, v[12:15], s[6:7] offset:3072
	s_add_u32 s6, s6, 0x4000
	s_addc_u32 s7, s7, 0
	s_cmp_eq_u32 s8, 7
	s_cbranch_scc1 .Lffill_tail
; DEV void final_norm_rows(float* __restrict__ X, const float* __restrict__ gvec, int rbeg) {
;     ...
;   for (int jb = 0; jb < 16; jb += 4) {
;     float4 v[4][4];
;     float ss[4];
; #pragma unroll
;     for (int j = 0; j < 4; ++j) {
;       const float* x = X + (long)(rbeg + wave + 4 * (jb + j)) * D;
; #pragma unroll
;       for (int i = 0; i < 4; ++i) v[j][i] = *(const float4*)(x + lane * 4 + 256 * i);
;     }
; #pragma unroll
;     for (int j = 0; j < 4; ++j) {
;       float t = 0.f;
; #pragma unroll
;       for (int i = 0; i < 4; ++i) t += v[j][i].x * v[j][i].x + v[j][i].y * v[j][i].y + v[j][i].z * v[j][i].z + v[j][i].w * v[j][i].w;
;       ss[j] = wave_sum(t);
;     }
; #pragma unroll
;     for (int j = 0; j < 4; ++j) {
;       float* x = X + (long)(rbeg + wave + 4 * (jb + j)) * D;
;       const float rstd = rsqrtf(ss[j] * (1.f / 1024.f) + EPSF);
; #pragma unroll
;       for (int i = 0; i < 4; ++i) {
;         const int k = lane * 4 + 256 * i;
;         const float4 g = *(const float4*)(gvec + k);
;         *(float4*)(x + k) = make_float4(v[j][i].x * rstd * g.x, v[j][i].y * rstd * g.y, v[j][i].z * rstd * g.z, v[j][i].w * rstd * g.w);
;       }
;     }
;   }
	s_lshl_b32 s5, s4, 12
	s_add_u32 s0, s78, s5
	s_addc_u32 s1, s79, 0
	global_load_dwordx4 v[0:3], v51, s[0:1]
	global_load_dwordx4 v[4:7], v51, s[0:1] offset:1024
	global_load_dwordx4 v[8:11], v51, s[0:1] offset:2048
	global_load_dwordx4 v[12:15], v51, s[0:1] offset:3072
	s_add_u32 s4, s4, 0x4
	s_waitcnt vmcnt(8)
	v_mul_f32_e32 v48, v16, v16
	v_fmac_f32_e32 v48, v17, v17
	v_fmac_f32_e32 v48, v18, v18
	v_fmac_f32_e32 v48, v19, v19
	v_fmac_f32_e32 v48, v20, v20
	v_fmac_f32_e32 v48, v21, v21
	v_fmac_f32_e32 v48, v22, v22
	v_fmac_f32_e32 v48, v23, v23
	v_fmac_f32_e32 v48, v24, v24
	v_fmac_f32_e32 v48, v25, v25
	v_fmac_f32_e32 v48, v26, v26
	v_fmac_f32_e32 v48, v27, v27
	v_fmac_f32_e32 v48, v28, v28
	v_fmac_f32_e32 v48, v29, v29
	v_fmac_f32_e32 v48, v30, v30
	v_fmac_f32_e32 v48, v31, v31
	s_nop 1
	v_add_f32_dpp v48, v48, v48 quad_perm:[1,0,3,2] row_mask:0xf bank_mask:0xf
	s_nop 1
	v_add_f32_dpp v48, v48, v48 quad_perm:[2,3,0,1] row_mask:0xf bank_mask:0xf
	s_nop 1
	v_add_f32_dpp v48, v48, v48 row_half_mirror row_mask:0xf bank_mask:0xf
	s_nop 1
	v_add_f32_dpp v48, v48, v48 row_mirror row_mask:0xf bank_mask:0xf
	s_nop 1
	v_add_f32_dpp v48, v48, v48 row_bcast:15 row_mask:0xa bank_mask:0xf
	s_nop 1
	v_add_f32_dpp v48, v48, v48 row_bcast:31 row_mask:0xc bank_mask:0xf
	s_nop 1
	v_readlane_b32 s5, v48, 63
	v_mov_b32_e32 v49, 0x3a800000
	s_nop 1
	v_fma_f32 v52, s5, v49, v53
	v_cmp_gt_f32_e32 vcc, 0x800000, v52
	v_mul_f32_e32 v50, 0x4b800000, v52
	v_cndmask_b32_e32 v52, v52, v50, vcc
	v_rsq_f32_e32 v52, v52
	s_nop 0
	v_mul_f32_e32 v50, 0x45800000, v52
	v_cndmask_b32_e32 v52, v52, v50, vcc
	v_mul_f32_e32 v16, v16, v52
	v_mul_f32_e32 v16, v16, v32
	v_mul_f32_e32 v17, v17, v52
	v_mul_f32_e32 v17, v17, v33
	v_mul_f32_e32 v18, v18, v52
	v_mul_f32_e32 v18, v18, v34
	v_mul_f32_e32 v19, v19, v52
	v_mul_f32_e32 v19, v19, v35
	v_mul_f32_e32 v20, v20, v52
	v_mul_f32_e32 v20, v20, v36
	v_mul_f32_e32 v21, v21, v52
	v_mul_f32_e32 v21, v21, v37
	v_mul_f32_e32 v22, v22, v52
	v_mul_f32_e32 v22, v22, v38
	v_mul_f32_e32 v23, v23, v52
	v_mul_f32_e32 v23, v23, v39
	v_mul_f32_e32 v24, v24, v52
	v_mul_f32_e32 v24, v24, v40
	v_mul_f32_e32 v25, v25, v52
	v_mul_f32_e32 v25, v25, v41
	v_mul_f32_e32 v26, v26, v52
	v_mul_f32_e32 v26, v26, v42
	v_mul_f32_e32 v27, v27, v52
	v_mul_f32_e32 v27, v27, v43
	v_mul_f32_e32 v28, v28, v52
	v_mul_f32_e32 v28, v28, v44
	v_mul_f32_e32 v29, v29, v52
	v_mul_f32_e32 v29, v29, v45
	v_mul_f32_e32 v30, v30, v52
	v_mul_f32_e32 v30, v30, v46
	v_mul_f32_e32 v31, v31, v52
	v_mul_f32_e32 v31, v31, v47
	global_store_dwordx4 v51, v[16:19], s[6:7]
	global_store_dwordx4 v51, v[20:23], s[6:7] offset:1024
	global_store_dwordx4 v51, v[24:27], s[6:7] offset:2048
	global_store_dwordx4 v51, v[28:31], s[6:7] offset:3072
	s_add_u32 s6, s6, 0x4000
	s_addc_u32 s7, s7, 0
	s_lshl_b32 s5, s4, 12
	s_add_u32 s0, s78, s5
	s_addc_u32 s1, s79, 0
	global_load_dwordx4 v[16:19], v51, s[0:1]
	global_load_dwordx4 v[20:23], v51, s[0:1] offset:1024
	global_load_dwordx4 v[24:27], v51, s[0:1] offset:2048
	global_load_dwordx4 v[28:31], v51, s[0:1] offset:3072
	s_add_u32 s4, s4, 0x4
	s_add_u32 s8, s8, 1
	s_branch .Lffill_loop
.Lffill_tail:
	s_waitcnt vmcnt(4)
	v_mul_f32_e32 v48, v16, v16
	v_fmac_f32_e32 v48, v17, v17
	v_fmac_f32_e32 v48, v18, v18
	v_fmac_f32_e32 v48, v19, v19
	v_fmac_f32_e32 v48, v20, v20
	v_fmac_f32_e32 v48, v21, v21
	v_fmac_f32_e32 v48, v22, v22
	v_fmac_f32_e32 v48, v23, v23
	v_fmac_f32_e32 v48, v24, v24
	v_fmac_f32_e32 v48, v25, v25
	v_fmac_f32_e32 v48, v26, v26
	v_fmac_f32_e32 v48, v27, v27
	v_fmac_f32_e32 v48, v28, v28
	v_fmac_f32_e32 v48, v29, v29
	v_fmac_f32_e32 v48, v30, v30
	v_fmac_f32_e32 v48, v31, v31
	s_nop 1
	v_add_f32_dpp v48, v48, v48 quad_perm:[1,0,3,2] row_mask:0xf bank_mask:0xf
	s_nop 1
	v_add_f32_dpp v48, v48, v48 quad_perm:[2,3,0,1] row_mask:0xf bank_mask:0xf
	s_nop 1
	v_add_f32_dpp v48, v48, v48 row_half_mirror row_mask:0xf bank_mask:0xf
	s_nop 1
	v_add_f32_dpp v48, v48, v48 row_mirror row_mask:0xf bank_mask:0xf
	s_nop 1
	v_add_f32_dpp v48, v48, v48 row_bcast:15 row_mask:0xa bank_mask:0xf
	s_nop 1
	v_add_f32_dpp v48, v48, v48 row_bcast:31 row_mask:0xc bank_mask:0xf
	s_nop 1
	v_readlane_b32 s5, v48, 63
	v_mov_b32_e32 v49, 0x3a800000
	s_nop 1
	v_fma_f32 v52, s5, v49, v53
	v_cmp_gt_f32_e32 vcc, 0x800000, v52
	v_mul_f32_e32 v50, 0x4b800000, v52
	v_cndmask_b32_e32 v52, v52, v50, vcc
	v_rsq_f32_e32 v52, v52
	s_nop 0
	v_mul_f32_e32 v50, 0x45800000, v52
	v_cndmask_b32_e32 v52, v52, v50, vcc
	v_mul_f32_e32 v16, v16, v52
	v_mul_f32_e32 v16, v16, v32
	v_mul_f32_e32 v17, v17, v52
	v_mul_f32_e32 v17, v17, v33
	v_mul_f32_e32 v18, v18, v52
	v_mul_f32_e32 v18, v18, v34
	v_mul_f32_e32 v19, v19, v52
	v_mul_f32_e32 v19, v19, v35
	v_mul_f32_e32 v20, v20, v52
	v_mul_f32_e32 v20, v20, v36
	v_mul_f32_e32 v21, v21, v52
	v_mul_f32_e32 v21, v21, v37
	v_mul_f32_e32 v22, v22, v52
	v_mul_f32_e32 v22, v22, v38
	v_mul_f32_e32 v23, v23, v52
	v_mul_f32_e32 v23, v23, v39
	v_mul_f32_e32 v24, v24, v52
	v_mul_f32_e32 v24, v24, v40
	v_mul_f32_e32 v25, v25, v52
	v_mul_f32_e32 v25, v25, v41
	v_mul_f32_e32 v26, v26, v52
	v_mul_f32_e32 v26, v26, v42
	v_mul_f32_e32 v27, v27, v52
	v_mul_f32_e32 v27, v27, v43
	v_mul_f32_e32 v28, v28, v52
	v_mul_f32_e32 v28, v28, v44
	v_mul_f32_e32 v29, v29, v52
	v_mul_f32_e32 v29, v29, v45
	v_mul_f32_e32 v30, v30, v52
	v_mul_f32_e32 v30, v30, v46
	v_mul_f32_e32 v31, v31, v52
	v_mul_f32_e32 v31, v31, v47
	global_store_dwordx4 v51, v[16:19], s[6:7]
	global_store_dwordx4 v51, v[20:23], s[6:7] offset:1024
	global_store_dwordx4 v51, v[24:27], s[6:7] offset:2048
	global_store_dwordx4 v51, v[28:31], s[6:7] offset:3072
	s_add_u32 s6, s6, 0x4000
	s_addc_u32 s7, s7, 0
	s_waitcnt vmcnt(0)
	s_mov_b64 s[0:1], 0

; DEV int tidx() { return tidx_full() & 255; }
; #define VBID ((int)blockIdx.x * 2 + vhalf())
; DEV void phase_final_norm(float* __restrict__ X, const float* __restrict__ gvec) {
;   const int tid = tidx();
;   const int wave = tid >> 6, lane = tid & 63;
;   constexpr int RB = 4;
;   const int stride = NVB * 4;
;   for (int row0 = VBID * 4 + wave; row0 < NTOK; row0 += stride * RB) {
;     float4 v[RB][4];
;     float ss[RB];
; #pragma unroll
;     for (int j = 0; j < RB; ++j) {
;       const int row = row0 + j * stride;
;       const float* x = X + (long)(row < NTOK ? row : row0) * D;
; #pragma unroll
;       for (int i = 0; i < 4; ++i) v[j][i] = *(const float4*)(x + lane * 4 + 256 * i);
;     }
; #pragma unroll
;     for (int j = 0; j < RB; ++j) {
;       float t = 0.f;
; #pragma unroll
;       for (int i = 0; i < 4; ++i) t += v[j][i].x * v[j][i].x + v[j][i].y * v[j][i].y + v[j][i].z * v[j][i].z + v[j][i].w * v[j][i].w;
;       ss[j] = wave_sum(t);
;     }
; #pragma unroll
;     for (int j = 0; j < RB; ++j) {
;       const int row = row0 + j * stride;
;       if (row < NTOK) {
;         const float rstd = rsqrtf(ss[j] * (1.f / 1024.f) + EPSF);
;         float* x = X + (long)row * D;
; #pragma unroll
;         for (int i = 0; i < 4; ++i) {
;           const int k = lane * 4 + 256 * i;
;           const float4 g = *(const float4*)(gvec + k);
;           *(float4*)(x + k) = make_float4(v[j][i].x * rstd * g.x, v[j][i].y * rstd * g.y, v[j][i].z * rstd * g.z, v[j][i].w * rstd * g.w);
;         }
;       }
;     }
;   }
; }
.LBB0_1242:
	v_readfirstlane_b32 s0, v202
	s_lshr_b32 s0, s0, 6
	s_waitcnt vmcnt(1)
	v_mov_b32_e32 v17, v202
	s_and_b32 s0, s0, 0x3fffffc
	s_add_i32 s1, s0, s95
	v_bfe_u32 v16, v17, 6, 2
	v_or_b32_e32 v64, s1, v16
	s_mov_b32 s10, 0x8000
	v_cmp_gt_i32_e32 vcc, s10, v64
	s_and_saveexec_b64 s[2:3], vcc
	s_cbranch_execz .LBB0_1251
	v_readfirstlane_b32 s4, v202
	s_lshr_b32 s4, s4, 6
	s_lshl_b32 s8, s80, 3
	s_add_u32 s4, s4, s8
	v_mov_b32_e32 v53, 0x358637bd
	v_and_b32_e32 v51, 63, v202
	v_lshlrev_b32_e32 v51, 4, v51
	global_load_dwordx4 v[32:35], v51, s[76:77]
	global_load_dwordx4 v[36:39], v51, s[76:77] offset:1024
	global_load_dwordx4 v[40:43], v51, s[76:77] offset:2048
	global_load_dwordx4 v[44:47], v51, s[76:77] offset:3072
	s_lshl_b32 s5, s4, 12
	s_add_u32 s6, s28, s5
	s_addc_u32 s7, s29, 0
	s_lshl_b32 s5, s4, 12
	s_add_u32 s0, s28, s5
	s_addc_u32 s1, s29, 0
	global_load_dwordx4 v[0:3], v51, s[0:1]
	global_load_dwordx4 v[4:7], v51, s[0:1] offset:1024
	global_load_dwordx4 v[8:11], v51, s[0:1] offset:2048
	global_load_dwordx4 v[12:15], v51, s[0:1] offset:3072
	s_add_u32 s4, s4, 0x800
	s_lshl_b32 s5, s4, 12
	s_add_u32 s0, s28, s5
	s_addc_u32 s1, s29, 0
	global_load_dwordx4 v[16:19], v51, s[0:1]
	global_load_dwordx4 v[20:23], v51, s[0:1] offset:1024
	global_load_dwordx4 v[24:27], v51, s[0:1] offset:2048
	global_load_dwordx4 v[28:31], v51, s[0:1] offset:3072
	s_add_u32 s4, s4, 0x800
	s_mov_b32 s8, 0
.Lfnorm_loop:
	s_waitcnt vmcnt(4)
	v_mul_f32_e32 v48, v0, v0
	v_fmac_f32_e32 v48, v1, v1
	v_fmac_f32_e32 v48, v2, v2
	v_fmac_f32_e32 v48, v3, v3
	v_fmac_f32_e32 v48, v4, v4
	v_fmac_f32_e32 v48, v5, v5
	v_fmac_f32_e32 v48, v6, v6
	v_fmac_f32_e32 v48, v7, v7
	v_fmac_f32_e32 v48, v8, v8
	v_fmac_f32_e32 v48, v9, v9
	v_fmac_f32_e32 v48, v10, v10
	v_fmac_f32_e32 v48, v11, v11
	v_fmac_f32_e32 v48, v12, v12
	v_fmac_f32_e32 v48, v13, v13
	v_fmac_f32_e32 v48, v14, v14
	v_fmac_f32_e32 v48, v15, v15
	s_nop 1
	v_add_f32_dpp v48, v48, v48 quad_perm:[1,0,3,2] row_mask:0xf bank_mask:0xf
	s_nop 1
	v_add_f32_dpp v48, v48, v48 quad_perm:[2,3,0,1] row_mask:0xf bank_mask:0xf
	s_nop 1
	v_add_f32_dpp v48, v48, v48 row_half_mirror row_mask:0xf bank_mask:0xf
	s_nop 1
	v_add_f32_dpp v48, v48, v48 row_mirror row_mask:0xf bank_mask:0xf
	s_nop 1
	v_add_f32_dpp v48, v48, v48 row_bcast:15 row_mask:0xa bank_mask:0xf
	s_nop 1
	v_add_f32_dpp v48, v48, v48 row_bcast:31 row_mask:0xc bank_mask:0xf
	s_nop 1
	v_readlane_b32 s5, v48, 63
	v_mov_b32_e32 v49, 0x3a800000
	s_nop 1
	v_fma_f32 v52, s5, v49, v53
	v_cmp_gt_f32_e32 vcc, 0x800000, v52
	v_mul_f32_e32 v50, 0x4b800000, v52
	v_cndmask_b32_e32 v52, v52, v50, vcc
	v_rsq_f32_e32 v52, v52
	s_nop 0
	v_mul_f32_e32 v50, 0x45800000, v52
	v_cndmask_b32_e32 v52, v52, v50, vcc
	v_mul_f32_e32 v0, v0, v52
	v_mul_f32_e32 v0, v0, v32
	v_mul_f32_e32 v1, v1, v52
	v_mul_f32_e32 v1, v1, v33
	v_mul_f32_e32 v2, v2, v52
	v_mul_f32_e32 v2, v2, v34
	v_mul_f32_e32 v3, v3, v52
	v_mul_f32_e32 v3, v3, v35
	v_mul_f32_e32 v4, v4, v52
	v_mul_f32_e32 v4, v4, v36
	v_mul_f32_e32 v5, v5, v52
	v_mul_f32_e32 v5, v5, v37
	v_mul_f32_e32 v6, v6, v52
	v_mul_f32_e32 v6, v6, v38
	v_mul_f32_e32 v7, v7, v52
	v_mul_f32_e32 v7, v7, v39
	v_mul_f32_e32 v8, v8, v52
	v_mul_f32_e32 v8, v8, v40
	v_mul_f32_e32 v9, v9, v52
	v_mul_f32_e32 v9, v9, v41
	v_mul_f32_e32 v10, v10, v52
	v_mul_f32_e32 v10, v10, v42
	v_mul_f32_e32 v11, v11, v52
	v_mul_f32_e32 v11, v11, v43
	v_mul_f32_e32 v12, v12, v52
	v_mul_f32_e32 v12, v12, v44
	v_mul_f32_e32 v13, v13, v52
	v_mul_f32_e32 v13, v13, v45
	v_mul_f32_e32 v14, v14, v52
	v_mul_f32_e32 v14, v14, v46
	v_mul_f32_e32 v15, v15, v52
	v_mul_f32_e32 v15, v15, v47
	global_store_dwordx4 v51, v[0:3], s[6:7]
	global_store_dwordx4 v51, v[4:7], s[6:7] offset:1024
	global_store_dwordx4 v51, v[8:11], s[6:7] offset:2048
	global_store_dwordx4 v51, v[12:15], s[6:7] offset:3072
	s_add_u32 s6, s6, 0x800000
	s_addc_u32 s7, s7, 0
	s_cmp_eq_u32 s8, 7
	s_cbranch_scc1 .Lfnorm_tail
; DEV int tidx() { return tidx_full() & 255; }
; #define VBID ((int)blockIdx.x * 2 + vhalf())
; DEV void phase_final_norm(float* __restrict__ X, const float* __restrict__ gvec) {
;   const int tid = tidx();
;   const int wave = tid >> 6, lane = tid & 63;
;   constexpr int RB = 4;
;   const int stride = NVB * 4;
;   for (int row0 = VBID * 4 + wave; row0 < NTOK; row0 += stride * RB) {
;     float4 v[RB][4];
;     float ss[RB];
; #pragma unroll
;     for (int j = 0; j < RB; ++j) {
;       const int row = row0 + j * stride;
;       const float* x = X + (long)(row < NTOK ? row : row0) * D;
; #pragma unroll
;       for (int i = 0; i < 4; ++i) v[j][i] = *(const float4*)(x + lane * 4 + 256 * i);
;     }
; #pragma unroll
;     for (int j = 0; j < RB; ++j) {
;       float t = 0.f;
; #pragma unroll
;       for (int i = 0; i < 4; ++i) t += v[j][i].x * v[j][i].x + v[j][i].y * v[j][i].y + v[j][i].z * v[j][i].z + v[j][i].w * v[j][i].w;
;       ss[j] = wave_sum(t);
;     }
; #pragma unroll
;     for (int j = 0; j < RB; ++j) {
;       const int row = row0 + j * stride;
;       if (row < NTOK) {
;         const float rstd = rsqrtf(ss[j] * (1.f / 1024.f) + EPSF);
;         float* x = X + (long)row * D;
; #pragma unroll
;         for (int i = 0; i < 4; ++i) {
;           const int k = lane * 4 + 256 * i;
;           const float4 g = *(const float4*)(gvec + k);
;           *(float4*)(x + k) = make_float4(v[j][i].x * rstd * g.x, v[j][i].y * rstd * g.y, v[j][i].z * rstd * g.z, v[j][i].w * rstd * g.w);
;         }
;       }
;     }
;   }
; }
	s_lshl_b32 s5, s4, 12
	s_add_u32 s0, s28, s5
	s_addc_u32 s1, s29, 0
	global_load_dwordx4 v[0:3], v51, s[0:1]
	global_load_dwordx4 v[4:7], v51, s[0:1] offset:1024
	global_load_dwordx4 v[8:11], v51, s[0:1] offset:2048
	global_load_dwordx4 v[12:15], v51, s[0:1] offset:3072
	s_add_u32 s4, s4, 0x800
	s_waitcnt vmcnt(8)
	v_mul_f32_e32 v48, v16, v16
	v_fmac_f32_e32 v48, v17, v17
	v_fmac_f32_e32 v48, v18, v18
	v_fmac_f32_e32 v48, v19, v19
	v_fmac_f32_e32 v48, v20, v20
	v_fmac_f32_e32 v48, v21, v21
	v_fmac_f32_e32 v48, v22, v22
	v_fmac_f32_e32 v48, v23, v23
	v_fmac_f32_e32 v48, v24, v24
	v_fmac_f32_e32 v48, v25, v25
	v_fmac_f32_e32 v48, v26, v26
	v_fmac_f32_e32 v48, v27, v27
	v_fmac_f32_e32 v48, v28, v28
	v_fmac_f32_e32 v48, v29, v29
	v_fmac_f32_e32 v48, v30, v30
	v_fmac_f32_e32 v48, v31, v31
	s_nop 1
	v_add_f32_dpp v48, v48, v48 quad_perm:[1,0,3,2] row_mask:0xf bank_mask:0xf
	s_nop 1
	v_add_f32_dpp v48, v48, v48 quad_perm:[2,3,0,1] row_mask:0xf bank_mask:0xf
	s_nop 1
	v_add_f32_dpp v48, v48, v48 row_half_mirror row_mask:0xf bank_mask:0xf
	s_nop 1
	v_add_f32_dpp v48, v48, v48 row_mirror row_mask:0xf bank_mask:0xf
	s_nop 1
	v_add_f32_dpp v48, v48, v48 row_bcast:15 row_mask:0xa bank_mask:0xf
	s_nop 1
	v_add_f32_dpp v48, v48, v48 row_bcast:31 row_mask:0xc bank_mask:0xf
	s_nop 1
	v_readlane_b32 s5, v48, 63
	v_mov_b32_e32 v49, 0x3a800000
	s_nop 1
	v_fma_f32 v52, s5, v49, v53
	v_cmp_gt_f32_e32 vcc, 0x800000, v52
	v_mul_f32_e32 v50, 0x4b800000, v52
	v_cndmask_b32_e32 v52, v52, v50, vcc
	v_rsq_f32_e32 v52, v52
	s_nop 0
	v_mul_f32_e32 v50, 0x45800000, v52
	v_cndmask_b32_e32 v52, v52, v50, vcc
	v_mul_f32_e32 v16, v16, v52
	v_mul_f32_e32 v16, v16, v32
	v_mul_f32_e32 v17, v17, v52
	v_mul_f32_e32 v17, v17, v33
	v_mul_f32_e32 v18, v18, v52
	v_mul_f32_e32 v18, v18, v34
	v_mul_f32_e32 v19, v19, v52
	v_mul_f32_e32 v19, v19, v35
	v_mul_f32_e32 v20, v20, v52
	v_mul_f32_e32 v20, v20, v36
	v_mul_f32_e32 v21, v21, v52
	v_mul_f32_e32 v21, v21, v37
	v_mul_f32_e32 v22, v22, v52
	v_mul_f32_e32 v22, v22, v38
	v_mul_f32_e32 v23, v23, v52
	v_mul_f32_e32 v23, v23, v39
	v_mul_f32_e32 v24, v24, v52
	v_mul_f32_e32 v24, v24, v40
	v_mul_f32_e32 v25, v25, v52
	v_mul_f32_e32 v25, v25, v41
	v_mul_f32_e32 v26, v26, v52
	v_mul_f32_e32 v26, v26, v42
	v_mul_f32_e32 v27, v27, v52
	v_mul_f32_e32 v27, v27, v43
	v_mul_f32_e32 v28, v28, v52
	v_mul_f32_e32 v28, v28, v44
	v_mul_f32_e32 v29, v29, v52
	v_mul_f32_e32 v29, v29, v45
	v_mul_f32_e32 v30, v30, v52
	v_mul_f32_e32 v30, v30, v46
	v_mul_f32_e32 v31, v31, v52
	v_mul_f32_e32 v31, v31, v47
	global_store_dwordx4 v51, v[16:19], s[6:7]
	global_store_dwordx4 v51, v[20:23], s[6:7] offset:1024
	global_store_dwordx4 v51, v[24:27], s[6:7] offset:2048
	global_store_dwordx4 v51, v[28:31], s[6:7] offset:3072
	s_add_u32 s6, s6, 0x800000
	s_addc_u32 s7, s7, 0
	s_lshl_b32 s5, s4, 12
	s_add_u32 s0, s28, s5
	s_addc_u32 s1, s29, 0
	global_load_dwordx4 v[16:19], v51, s[0:1]
	global_load_dwordx4 v[20:23], v51, s[0:1] offset:1024
	global_load_dwordx4 v[24:27], v51, s[0:1] offset:2048
	global_load_dwordx4 v[28:31], v51, s[0:1] offset:3072
	s_add_u32 s4, s4, 0x800
	s_add_u32 s8, s8, 1
	s_branch .Lfnorm_loop
.Lfnorm_tail:
	s_waitcnt vmcnt(4)
	v_mul_f32_e32 v48, v16, v16
	v_fmac_f32_e32 v48, v17, v17
	v_fmac_f32_e32 v48, v18, v18
	v_fmac_f32_e32 v48, v19, v19
	v_fmac_f32_e32 v48, v20, v20
	v_fmac_f32_e32 v48, v21, v21
	v_fmac_f32_e32 v48, v22, v22
	v_fmac_f32_e32 v48, v23, v23
	v_fmac_f32_e32 v48, v24, v24
	v_fmac_f32_e32 v48, v25, v25
	v_fmac_f32_e32 v48, v26, v26
	v_fmac_f32_e32 v48, v27, v27
	v_fmac_f32_e32 v48, v28, v28
	v_fmac_f32_e32 v48, v29, v29
	v_fmac_f32_e32 v48, v30, v30
	v_fmac_f32_e32 v48, v31, v31
	s_nop 1
	v_add_f32_dpp v48, v48, v48 quad_perm:[1,0,3,2] row_mask:0xf bank_mask:0xf
	s_nop 1
	v_add_f32_dpp v48, v48, v48 quad_perm:[2,3,0,1] row_mask:0xf bank_mask:0xf
	s_nop 1
	v_add_f32_dpp v48, v48, v48 row_half_mirror row_mask:0xf bank_mask:0xf
	s_nop 1
	v_add_f32_dpp v48, v48, v48 row_mirror row_mask:0xf bank_mask:0xf
	s_nop 1
	v_add_f32_dpp v48, v48, v48 row_bcast:15 row_mask:0xa bank_mask:0xf
	s_nop 1
	v_add_f32_dpp v48, v48, v48 row_bcast:31 row_mask:0xc bank_mask:0xf
	s_nop 1
	v_readlane_b32 s5, v48, 63
	v_mov_b32_e32 v49, 0x3a800000
	s_nop 1
	v_fma_f32 v52, s5, v49, v53
	v_cmp_gt_f32_e32 vcc, 0x800000, v52
	v_mul_f32_e32 v50, 0x4b800000, v52
	v_cndmask_b32_e32 v52, v52, v50, vcc
	v_rsq_f32_e32 v52, v52
	s_nop 0
	v_mul_f32_e32 v50, 0x45800000, v52
	v_cndmask_b32_e32 v52, v52, v50, vcc
	v_mul_f32_e32 v16, v16, v52
	v_mul_f32_e32 v16, v16, v32
	v_mul_f32_e32 v17, v17, v52
	v_mul_f32_e32 v17, v17, v33
	v_mul_f32_e32 v18, v18, v52
	v_mul_f32_e32 v18, v18, v34
	v_mul_f32_e32 v19, v19, v52
	v_mul_f32_e32 v19, v19, v35
	v_mul_f32_e32 v20, v20, v52
	v_mul_f32_e32 v20, v20, v36
	v_mul_f32_e32 v21, v21, v52
	v_mul_f32_e32 v21, v21, v37
	v_mul_f32_e32 v22, v22, v52
	v_mul_f32_e32 v22, v22, v38
	v_mul_f32_e32 v23, v23, v52
	v_mul_f32_e32 v23, v23, v39
	v_mul_f32_e32 v24, v24, v52
	v_mul_f32_e32 v24, v24, v40
	v_mul_f32_e32 v25, v25, v52
	v_mul_f32_e32 v25, v25, v41
	v_mul_f32_e32 v26, v26, v52
	v_mul_f32_e32 v26, v26, v42
	v_mul_f32_e32 v27, v27, v52
	v_mul_f32_e32 v27, v27, v43
	v_mul_f32_e32 v28, v28, v52
	v_mul_f32_e32 v28, v28, v44
	v_mul_f32_e32 v29, v29, v52
	v_mul_f32_e32 v29, v29, v45
	v_mul_f32_e32 v30, v30, v52
	v_mul_f32_e32 v30, v30, v46
	v_mul_f32_e32 v31, v31, v52
	v_mul_f32_e32 v31, v31, v47
	global_store_dwordx4 v51, v[16:19], s[6:7]
	global_store_dwordx4 v51, v[20:23], s[6:7] offset:1024
	global_store_dwordx4 v51, v[24:27], s[6:7] offset:2048
	global_store_dwordx4 v51, v[28:31], s[6:7] offset:3072
	s_add_u32 s6, s6, 0x800000
	s_addc_u32 s7, s7, 0
